# v12 + phase D QK/PV gathers: 32-bit per-lane offsets on an SGPR base (1 VALU per key instead of three 64-bit adds)
# speedup vs baseline: 1.0373x; 1.0078x over previous
.LBB0_779:
	s_cmp_gt_u32 s22, 14
	v_lshlrev_b32_e32 v64, 1, v146
	s_waitcnt vmcnt(7)
	ds_write_b128 v73, v[0:3] offset:8192
	s_waitcnt vmcnt(6)
	ds_write_b128 v74, v[4:7] offset:9216
	s_waitcnt vmcnt(5)
	ds_write_b128 v75, v[8:11] offset:10240
	s_waitcnt vmcnt(4)
	ds_write_b128 v76, v[12:15] offset:11264
	s_waitcnt vmcnt(3)
	ds_write_b128 v73, v[16:19] offset:12288
	s_waitcnt vmcnt(2)
	ds_write_b128 v74, v[20:23] offset:13312
	s_waitcnt vmcnt(1)
	ds_write_b128 v75, v[24:27] offset:14336
	s_waitcnt vmcnt(0)
	ds_write_b128 v76, v[36:39] offset:15360
	s_cbranch_scc1 .LBB0_781
	s_add_i32 s20, s24, s2
	s_and_b32 s20, s20, 0xe0
	v_lshl_add_u32 v0, s20, 1, v72
	ds_read_u16 v1, v0
	ds_read_u16 v2, v0 offset:8
	ds_read_u16 v8, v0 offset:16
	ds_read_u16 v10, v0 offset:24
	ds_read_u16 v16, v0 offset:32
	ds_read_u16 v18, v0 offset:40
	ds_read_u16 v24, v0 offset:48
	ds_read_u16 v26, v0 offset:56
	s_and_b32 s20, s23, 0x180
	s_lshl_b32 s46, s20, 1
	v_add_u32_e32 v136, s46, v64
	s_waitcnt lgkmcnt(7)
	v_lshl_add_u32 v0, v1, 9, v136
	s_waitcnt lgkmcnt(6)
	v_lshl_add_u32 v4, v2, 9, v136
	s_waitcnt lgkmcnt(5)
	v_lshl_add_u32 v8, v8, 9, v136
	s_waitcnt lgkmcnt(4)
	v_lshl_add_u32 v12, v10, 9, v136
	s_waitcnt lgkmcnt(3)
	v_lshl_add_u32 v16, v16, 9, v136
	s_waitcnt lgkmcnt(2)
	v_lshl_add_u32 v20, v18, 9, v136
	s_waitcnt lgkmcnt(1)
	v_lshl_add_u32 v24, v24, 9, v136
	s_waitcnt lgkmcnt(0)
	v_lshl_add_u32 v36, v26, 9, v136
	global_load_dwordx4 v[0:3], v0, s[48:49]
	s_nop 0
	global_load_dwordx4 v[4:7], v4, s[48:49]
	s_nop 0
	global_load_dwordx4 v[8:11], v8, s[48:49]
	s_nop 0
	global_load_dwordx4 v[12:15], v12, s[48:49]
	s_nop 0
	global_load_dwordx4 v[16:19], v16, s[48:49]
	s_nop 0
	global_load_dwordx4 v[20:23], v20, s[48:49]
	s_nop 0
	global_load_dwordx4 v[24:27], v24, s[48:49]
	s_nop 0
	global_load_dwordx4 v[36:39], v36, s[48:49]

.LBB0_789:
	s_cmp_gt_u32 s20, 14
	s_waitcnt vmcnt(7)
	ds_write_b128 v73, v[0:3] offset:8192
	s_waitcnt vmcnt(6)
	ds_write_b128 v74, v[4:7] offset:9216
	s_waitcnt vmcnt(5)
	ds_write_b128 v75, v[8:11] offset:10240
	s_waitcnt vmcnt(4)
	ds_write_b128 v76, v[12:15] offset:11264
	s_waitcnt vmcnt(3)
	ds_write_b128 v73, v[16:19] offset:12288
	s_waitcnt vmcnt(2)
	ds_write_b128 v74, v[20:23] offset:13312
	s_waitcnt vmcnt(1)
	ds_write_b128 v75, v[24:27] offset:14336
	s_waitcnt vmcnt(0)
	ds_write_b128 v76, v[28:31] offset:15360
	s_cbranch_scc1 .LBB0_788
	s_and_b32 s24, s22, 0xe0
	v_lshl_add_u32 v0, s24, 1, v72
	ds_read_u16 v1, v0
	ds_read_u16 v2, v0 offset:8
	ds_read_u16 v8, v0 offset:16
	ds_read_u16 v10, v0 offset:24
	ds_read_u16 v16, v0 offset:32
	ds_read_u16 v18, v0 offset:40
	ds_read_u16 v24, v0 offset:48
	ds_read_u16 v26, v0 offset:56
	s_and_b32 s24, s21, 0x180
	s_lshl_b32 s46, s24, 1
	v_add_u32_e32 v136, s46, v64
	s_waitcnt lgkmcnt(7)
	v_lshl_add_u32 v0, v1, 9, v136
	s_waitcnt lgkmcnt(6)
	v_lshl_add_u32 v4, v2, 9, v136
	s_waitcnt lgkmcnt(5)
	v_lshl_add_u32 v8, v8, 9, v136
	s_waitcnt lgkmcnt(4)
	v_lshl_add_u32 v12, v10, 9, v136
	s_waitcnt lgkmcnt(3)
	v_lshl_add_u32 v16, v16, 9, v136
	s_waitcnt lgkmcnt(2)
	v_lshl_add_u32 v20, v18, 9, v136
	s_waitcnt lgkmcnt(1)
	v_lshl_add_u32 v24, v24, 9, v136
	s_waitcnt lgkmcnt(0)
	v_lshl_add_u32 v28, v26, 9, v136
	global_load_dwordx4 v[0:3], v0, s[54:55]
	s_nop 0
	global_load_dwordx4 v[4:7], v4, s[54:55]
	s_nop 0
	global_load_dwordx4 v[8:11], v8, s[54:55]
	s_nop 0
	global_load_dwordx4 v[12:15], v12, s[54:55]
	s_nop 0
	global_load_dwordx4 v[16:19], v16, s[54:55]
	s_nop 0
	global_load_dwordx4 v[20:23], v20, s[54:55]
	s_nop 0
	global_load_dwordx4 v[24:27], v24, s[54:55]
	s_nop 0
	global_load_dwordx4 v[28:31], v28, s[54:55]
	s_branch .LBB0_788
